# MoBA own-block phase: 4-wave group 1 runs its two query tiles in the opposite order (long tile first) so SIMD partner waves are out of phase
# speedup vs baseline: 1.0109x; 1.0109x over previous
; #define LAS __attribute__((address_space(3)))
; DI void phase_moba_own(const Args& A, unsigned char* lds, LAS unsigned char* lds3, int tid, int wid, int lane) {
;     const bf16_t* QKV = (const bf16_t*)(A.ws + WS_QKV); const unsigned* SEL = (const unsigned*)(A.ws + WS_SEL);
;     const bf16_t* PO = (const bf16_t*)(A.ws + WS_PO); const float* PML = (const float*)(A.ws + WS_PML); bf16_t* ATT = (bf16_t*)(A.ws + WS_ATT);
;     const int r32 = lane & 31, hi = lane >> 5, grp = wid >> 2, g4 = wid & 3;
;     unsigned char* ldsg = lds + grp * MB_GRP; LAS unsigned char* lds3g = lds3 + grp * MB_GRP;
;     for (int u0 = 2 * blockIdx.x; u0 < BATCH * 16 * 64; u0 += 2 * gridDim.x) {
;         const int u = u0 + grp, i = u & 63, bh = u >> 6, b = bh >> 4, h = bh & 15;
;         __syncthreads();
;         moba_stage_kv256(QKV, ldsg, b, h, i, tid & 255);
;         __syncthreads();
; #pragma unroll 1
;         for (int pass = 0; pass < 2; ++pass) {
;             const int tile = pass == 0 ? g4 : 7 - g4;
;             const int s = i * 256 + tile * 32 + r32;
;             bf16x8 qf[4];
; #pragma unroll
;             for (int c = 0; c < 4; ++c) qf[c] = *(const bf16x8*)(QKV + ((size_t)b * SEQ + s) * QKVW + h * 64 + 16 * c + 8 * hi);
;             f32x16 o[2];
; #pragma unroll
;             for (int k = 0; k < 16; ++k) { o[0][k] = 0.f; o[1][k] = 0.f; }
;             float m = -INFINITY, l = 0.f;
;             const unsigned w = SEL[(size_t)bh * SEQ + s];
;             const size_t pe0 = ((size_t)bh * SEQ + s) * 3;
;             float pm[3], pl[3]; u32x2 pw[3][8];
; #pragma unroll
;             for (int slot = 0; slot < 3; ++slot) {
;                 { typedef float f32x2_t __attribute__((ext_vector_type(2))); const f32x2_t ml = *(const f32x2_t*)(PML + (pe0 + slot) * 2); pm[slot] = ml.x; pl[slot] = ml.y; }
; #pragma unroll
;                 for (int dt = 0; dt < 2; ++dt)
; #pragma unroll
;                     for (int gp = 0; gp < 2; ++gp) { const u32x4 q4 = *(const u32x4*)(PO + (pe0 + slot) * 64 + hi * 32 + dt * 16 + gp * 8); pw[slot][dt * 4 + 2 * gp] = (u32x2){q4.x, q4.y}; pw[slot][dt * 4 + 2 * gp + 1] = (u32x2){q4.z, q4.w}; }
;             }
;             moba_tile(ldsg, lds3g, qf, tile + 1, tile, lane, o, m, l);
.LBB0_1369:
	s_cmp_gt_i32 s40, 11
	s_cselect_b64 s[4:5], -1, 0
	s_cmp_lt_i32 s41, 12
	s_cselect_b64 s[6:7], -1, 0
	s_or_b64 s[42:43], s[4:5], s[6:7]
	s_and_b64 vcc, exec, s[42:43]
	s_cbranch_vccnz .LBB0_1389
	s_mov_b64 s[4:5], s[0:1]
	v_mov_b32_e32 v2, v184
	s_lshl_b32 s3, s2, 1
	s_cmpk_gt_i32 s3, 0x7ff
	v_readfirstlane_b32 s6, v2
	s_cbranch_scc1 .LBB0_1389
	s_load_dwordx2 s[4:5], s[4:5], 0xa8
	s_waitcnt lgkmcnt(0)
	v_mov_b32_e32 v0, 3
	v_bfe_u32 v5, v2, 3, 5
	v_mov_b32_e32 v7, 0x78000
	v_lshlrev_b32_sdwa v0, v0, v2 dst_sel:DWORD dst_unused:UNUSED_PAD src0_sel:DWORD src1_sel:BYTE_0
	s_add_u32 s44, s4, 0x4000000
	s_addc_u32 s45, s5, 0
	s_add_u32 s46, s4, 0x2f00000
	s_addc_u32 s47, s5, 0
	s_add_u32 s48, s4, 0x3100000
	s_addc_u32 s49, s5, 0
	s_add_u32 s33, s4, 0x10000000
	s_addc_u32 s64, s5, 0
	s_ashr_i32 s65, s6, 8
	s_bfe_u32 s66, s6, 0x20006
	s_movk_i32 s6, 0xc00
	v_mad_u32_u24 v10, v5, s6, v7
	v_mov_b32_e32 v7, 0x90000
	v_and_b32_e32 v4, 56, v0
	v_mad_u32_u24 v12, v5, s6, v7
	v_mov_b32_e32 v7, 0xa8000
	v_lshlrev_b32_e32 v11, 12, v2
	v_and_b32_e32 v13, 0x7c0, v0
	v_lshrrev_b32_e32 v0, 1, v2
	s_mul_i32 s67, s65, 0x11000
	v_mov_b32_e32 v1, 0
	v_mad_u32_u24 v14, v5, s6, v7
	v_mov_b32_e32 v7, 4
	v_and_b32_e32 v11, 0x4000, v11
	v_and_b32_e32 v0, 16, v0
	v_lshlrev_b32_sdwa v7, v7, v2 dst_sel:DWORD dst_unused:UNUSED_PAD src0_sel:DWORD src1_sel:BYTE_0
	v_add_u32_e32 v11, s67, v11
	v_lshl_add_u64 v[134:135], s[44:45], 0, v[0:1]
	v_and_b32_e32 v0, 32, v2
	v_and_b32_e32 v9, 0x70, v7
	v_and_or_b32 v7, v7, 48, v11
	v_lshlrev_b32_e32 v0, 1, v0
	v_bfe_u32 v11, v2, 5, 1
	v_lshl_add_u64 v[16:17], s[4:5], 0, v[0:1]
	s_mov_b64 s[4:5], 0x14000000
	v_lshlrev_b32_e32 v0, 2, v11
	v_bfe_u32 v15, v2, 2, 2
	v_and_b32_e32 v158, 31, v2
	v_and_b32_e32 v3, 63, v2
	v_lshl_add_u64 v[136:137], v[16:17], 0, s[4:5]
	v_or_b32_e32 v16, v0, v15
	v_lshlrev_b32_e32 v17, 1, v2
	v_lshlrev_b32_e32 v2, 3, v2
	v_and_b32_e32 v17, 32, v17
	v_and_b32_e32 v18, 24, v2
	v_lshl_or_b32 v2, v16, 6, s67
	v_or3_b32 v159, v2, v17, v18
	v_mbcnt_lo_u32_b32 v2, -1, 0
	v_mbcnt_hi_u32_b32 v2, -1, v2
	s_load_dword s50, s[0:1], 0xb8
	v_and_b32_e32 v20, 64, v2
	v_xor_b32_e32 v16, 32, v2
	v_add_u32_e32 v20, 64, v20
	v_cmp_lt_i32_e32 vcc, v16, v20
	v_mul_u32_u24_e32 v6, 0xc00, v5
	v_sub_u32_e32 v0, v158, v0
	v_cndmask_b32_e32 v2, v2, v16, vcc
	v_cmp_lt_u32_e32 vcc, 31, v3
	v_lshlrev_b32_e32 v3, 6, v15
	v_or_b32_e32 v8, 0x60000, v6
	v_or_b32_e32 v9, s67, v9
	s_movk_i32 s71, 0x90
	v_mul_u32_u24_e32 v5, 0x90, v5
	v_lshlrev_b32_e32 v19, 4, v11
	v_lshlrev_b32_e32 v160, 2, v2
	v_cmp_gt_i32_e64 s[4:5], 0, v0
	v_cmp_gt_i32_e64 s[6:7], 1, v0
	v_cmp_gt_i32_e64 s[8:9], 2, v0
	v_cmp_gt_i32_e64 s[10:11], 3, v0
	v_cmp_gt_i32_e64 s[12:13], 8, v0
	v_cmp_gt_i32_e64 s[14:15], 9, v0
	v_cmp_gt_i32_e64 s[16:17], 10, v0
	v_cmp_gt_i32_e64 s[18:19], 11, v0
	v_cmp_gt_i32_e64 s[20:21], 16, v0
	v_cmp_gt_i32_e64 s[22:23], 17, v0
	v_cmp_gt_i32_e64 s[24:25], 18, v0
	v_cmp_gt_i32_e64 s[26:27], 19, v0
	v_cmp_gt_i32_e64 s[28:29], 24, v0
	v_cmp_gt_i32_e64 s[30:31], 25, v0
	v_cmp_gt_i32_e64 s[34:35], 26, v0
	v_cmp_gt_i32_e64 s[36:37], 27, v0
	v_cndmask_b32_e64 v0, 0, 8, vcc
	v_cndmask_b32_e64 v2, 16, 24, vcc
	v_lshl_or_b32 v3, v11, 8, v3
	s_movk_i32 s68, 0xff
	s_mov_b32 s69, 0x60000
	s_mov_b32 s70, 0x90000
	s_xor_b32 s72, s66, 7
	s_cmp_eq_u32 s65, 0
	s_cbranch_scc1 .Lown_noswap
	s_mov_b32 s72, s66
	s_xor_b32 s66, s66, 7
.Lown_noswap:
	s_mov_b32 s51, 0
	v_or_b32_e32 v161, s67, v19
	s_waitcnt lgkmcnt(0)
	s_lshl_b32 s73, s50, 1
	v_or3_b32 v162, v3, v17, v18
	v_mad_u32_u24 v163, v158, s71, v19
	s_movk_i32 s74, 0x1800
	v_lshlrev_b32_e32 v138, 1, v4
	v_mov_b32_e32 v139, v1
	v_lshlrev_b32_e32 v140, 1, v6
	v_mov_b32_e32 v141, v1
	s_mov_b32 s75, 0x30000
	v_lshlrev_b32_e32 v142, 1, v8
	v_mov_b32_e32 v143, v1
	v_lshlrev_b32_e32 v144, 1, v10
	v_mov_b32_e32 v145, v1
	v_lshlrev_b32_e32 v146, 1, v12
	v_mov_b32_e32 v147, v1
	v_lshlrev_b32_e32 v148, 1, v14
	v_mov_b32_e32 v149, v1
	v_add_u32_e32 v164, v9, v5
	s_mov_b64 s[52:53], 0x1000
	v_add_u32_e32 v165, v7, v13
	v_mov_b32_e32 v166, 0x1800
	s_movk_i32 s76, 0x180
	v_mov_b32_e32 v167, 0x180
	s_mov_b32 s77, 0x3e38aa3b
	s_mov_b32 s78, 0xff00
	s_mov_b32 s79, 0xff0000
	v_lshlrev_b32_e32 v150, 1, v0
	v_lshlrev_b32_e32 v152, 1, v2
	v_mov_b32_e32 v168, 0xff800000
	s_branch .LBB0_1373
